# attention phase: waves 4-7 staggered by s_sleep 8 after each unit's K/V staging barrier (two waves per SIMD no longer in lockstep)
# baseline (speedup 1.0000x reference)
; #define LAS __attribute__((address_space(3)))
; __device__ __forceinline__ void lds_barrier() { asm volatile("s_waitcnt lgkmcnt(0)\n\ts_barrier" ::: "memory"); }
; __device__ __forceinline__ int kswz(int row) { return (((row >> 1) & 3) << 1) | ((row >> 3) & 1); }
; __device__ __forceinline__ void attn_phase(bf16_t* QKV, float* LSE, const float* rel_table, LAS unsigned char* lds, int bx, int Gd, int tid) {
;     ...
;         for (int i = 0; i < 6; ++i) { const int ix = tid + 512 * i, row = ix >> 3, ch = ix & 7; const bool neg = (a.N0 - 128 + row) < 0;
;             const u32x4 z = (u32x4){0u, 0u, 0u, 0u};
;             *(LAS u32x4*)(lds + ATT_K + row * 128 + ((ch ^ kswz(row)) * 16)) = neg ? z : kr[i];
;             *(LAS u32x4*)(lds + ATT_V + row * 128 + ((((ch >> 1) ^ ((row >> 1) & 3)) * 32) + (ch & 1) * 16)) = neg ? z : vr[i]; }
;         bf16x8 qf[2][2];
; #pragma unroll
;         for (int qi = 0; qi < 2; ++qi) { qf[qi][0] = qn[qi][0]; qf[qi][1] = qn[qi][1]; }
;         const AttnGeom c = a;
;         lds_barrier();
.LBB0_116:
	s_sub_i32 s10, 0x80, s29
	v_cmp_gt_i32_e32 vcc, s10, v127
	v_add_u32_e32 v84, v141, v143
	s_add_i32 s25, s25, s6
	v_cndmask_b32_e64 v83, v3, 0, vcc
	v_cndmask_b32_e64 v82, v2, 0, vcc
	v_cndmask_b32_e64 v81, v1, 0, vcc
	v_cndmask_b32_e64 v80, v0, 0, vcc
	ds_write_b128 v157, v[80:83]
	v_cndmask_b32_e64 v83, v7, 0, vcc
	v_cndmask_b32_e64 v82, v6, 0, vcc
	v_cndmask_b32_e64 v81, v5, 0, vcc
	v_cndmask_b32_e64 v80, v4, 0, vcc
	v_cmp_gt_i32_e32 vcc, s10, v129
	ds_write_b128 v84, v[80:83] offset:49152
	v_add_u32_e32 v84, v141, v144
	v_cndmask_b32_e64 v83, v11, 0, vcc
	v_cndmask_b32_e64 v82, v10, 0, vcc
	v_cndmask_b32_e64 v81, v9, 0, vcc
	v_cndmask_b32_e64 v80, v8, 0, vcc
	ds_write_b128 v158, v[80:83]
	v_cndmask_b32_e64 v83, v15, 0, vcc
	v_cndmask_b32_e64 v82, v14, 0, vcc
	v_cndmask_b32_e64 v81, v13, 0, vcc
	v_cndmask_b32_e64 v80, v12, 0, vcc
	v_cmp_gt_i32_e32 vcc, s10, v131
	ds_write_b128 v84, v[80:83] offset:49152
	v_add_u32_e32 v84, v141, v145
	v_cndmask_b32_e64 v83, v19, 0, vcc
	v_cndmask_b32_e64 v82, v18, 0, vcc
	v_cndmask_b32_e64 v81, v17, 0, vcc
	v_cndmask_b32_e64 v80, v16, 0, vcc
	ds_write_b128 v159, v[80:83]
	v_cndmask_b32_e64 v83, v23, 0, vcc
	v_cndmask_b32_e64 v82, v22, 0, vcc
	v_cndmask_b32_e64 v81, v21, 0, vcc
	v_cndmask_b32_e64 v80, v20, 0, vcc
	v_cmp_gt_i32_e32 vcc, s10, v133
	ds_write_b128 v84, v[80:83] offset:49152
	v_add_u32_e32 v84, v141, v146
	v_cndmask_b32_e64 v83, v27, 0, vcc
	v_cndmask_b32_e64 v82, v26, 0, vcc
	v_cndmask_b32_e64 v81, v25, 0, vcc
	v_cndmask_b32_e64 v80, v24, 0, vcc
	ds_write_b128 v160, v[80:83]
	v_cndmask_b32_e64 v83, v31, 0, vcc
	v_cndmask_b32_e64 v82, v30, 0, vcc
	v_cndmask_b32_e64 v81, v29, 0, vcc
	v_cndmask_b32_e64 v80, v28, 0, vcc
	v_cmp_gt_i32_e32 vcc, s10, v135
	ds_write_b128 v84, v[80:83] offset:49152
	v_add_u32_e32 v84, v141, v147
	v_cndmask_b32_e64 v83, v35, 0, vcc
	v_cndmask_b32_e64 v82, v34, 0, vcc
	v_cndmask_b32_e64 v81, v33, 0, vcc
	v_cndmask_b32_e64 v80, v32, 0, vcc
	ds_write_b128 v161, v[80:83]
	v_cndmask_b32_e64 v83, v39, 0, vcc
	v_cndmask_b32_e64 v82, v38, 0, vcc
	v_cndmask_b32_e64 v81, v37, 0, vcc
	v_cndmask_b32_e64 v80, v36, 0, vcc
	v_cmp_gt_i32_e32 vcc, s10, v137
	ds_write_b128 v84, v[80:83] offset:49152
	v_add_u32_e32 v84, v141, v148
	v_cndmask_b32_e64 v83, v43, 0, vcc
	v_cndmask_b32_e64 v82, v42, 0, vcc
	v_cndmask_b32_e64 v81, v41, 0, vcc
	v_cndmask_b32_e64 v80, v40, 0, vcc
	ds_write_b128 v162, v[80:83]
	v_cndmask_b32_e64 v83, v47, 0, vcc
	v_cndmask_b32_e64 v82, v46, 0, vcc
	v_cndmask_b32_e64 v81, v45, 0, vcc
	v_cndmask_b32_e64 v80, v44, 0, vcc
	ds_write_b128 v84, v[80:83] offset:49152
	s_waitcnt lgkmcnt(0)
	s_barrier
	v_readfirstlane_b32 s98, v170
	s_nop 3
	s_bitcmp1_b32 s98, 8
	s_cbranch_scc0 .Lattn_nostag
	s_sleep 8
; __device__ __forceinline__ void attn_fetch(const bf16_t* QKV, const AttnGeom& a, int tid, u32x4 (&kr)[6], u32x4 (&vr)[6], bf16x8 (&qf)[2][2]) {
;     const int lane = tid & 63, w = tid >> 6, fr = lane & 15, G = lane >> 4;
; #pragma unroll
;     for (int i = 0; i < 6; ++i) { const int ix = tid + 512 * i, row = ix >> 3, ch = ix & 7; int step = a.N0 - 128 + row; step = step < 0 ? 0 : step;
;         const bf16_t* rp = QKV + (a.tok0 + (size_t)step * a.d) * NQKV + a.qcol + ch * 8; kr[i] = *(const u32x4*)(rp + 1536); vr[i] = *(const u32x4*)(rp + 3072); }
; #pragma unroll
;     for (int qi = 0; qi < 2; ++qi) { const bf16_t* qp = QKV + (a.tok0 + (size_t)(a.N0 + 32 * w + 16 * qi + fr) * a.d) * NQKV + a.qcol + 8 * G;
;         qf[qi][0] = *(const bf16x8*)qp; qf[qi][1] = *(const bf16x8*)(qp + 32); }
; }
; __device__ __forceinline__ void attn_phase(bf16_t* QKV, float* LSE, const float* rel_table, LAS unsigned char* lds, int bx, int Gd, int tid) {
;     ...
;         { const int nu = unit + Gd; if (nu < 3072) { a = attn_geom(nu); attn_fetch(QKV, a, tid, kr, vr, qn); } }
.Lattn_nostag:
	s_cmpk_gt_i32 s25, 0xbff
	s_cselect_b64 s[40:41], -1, 0
	s_and_b64 vcc, exec, s[40:41]
	s_mov_b32 s42, s34
	s_mov_b32 s48, s94
	s_mov_b32 s49, s28
	s_cbranch_vccnz .LBB0_118
	s_ashr_i32 s49, s25, 10
	s_lshl_b32 s13, s49, 1
	s_lshr_b32 s11, 32, s13
	s_bfe_u32 s10, s25, 0x50003
	s_add_i32 s11, s11, -1
	s_and_b32 s47, s11, s10
	s_sub_i32 s14, 5, s13
	s_lshl_b32 s46, s47, 8
	s_lshr_b32 s14, s10, s14
	s_lshl_b32 s10, s25, 5
	v_add_u32_e32 v0, s46, v128
	s_and_b32 s10, s10, 0x6000
	v_max_i32_e32 v168, 0, v0
	s_and_b32 s48, s25, 7
	s_or_b32 s38, s14, s10
	s_mov_b32 s39, s95
	v_lshlrev_b64 v[0:1], s13, v[168:169]
	v_add_u32_e32 v8, s46, v130
	s_lshl_b32 s10, s49, 9
	s_lshl_b32 s11, s48, 6
	v_lshl_add_u64 v[0:1], v[0:1], 0, s[38:39]
	v_mov_b64_e32 v[72:73], s[66:67]
	v_max_i32_e32 v168, 0, v8
	s_or_b32 s42, s10, s11
	v_mad_u64_u32 v[2:3], s[10:11], v0, s53, v[72:73]
	v_lshlrev_b64 v[8:9], s13, v[168:169]
	v_add_u32_e32 v16, s46, v132
	v_mov_b32_e32 v0, v3
	v_lshl_add_u64 v[8:9], v[8:9], 0, s[38:39]
	v_max_i32_e32 v168, 0, v16
	v_mad_u64_u32 v[0:1], s[10:11], v1, s53, v[0:1]
	s_ashr_i32 s43, s42, 31
	v_mad_u64_u32 v[10:11], s[14:15], v8, s53, v[72:73]
	v_lshlrev_b64 v[16:17], s13, v[168:169]
	v_add_u32_e32 v24, s46, v134
	v_mov_b32_e32 v3, v0
	s_lshl_b64 s[10:11], s[42:43], 1
	v_mov_b32_e32 v8, v11
	v_lshl_add_u64 v[16:17], v[16:17], 0, s[38:39]
	v_max_i32_e32 v168, 0, v24
	v_lshl_add_u64 v[0:1], v[2:3], 0, s[10:11]
	v_mov_b32_e32 v121, v169
	v_mad_u64_u32 v[8:9], s[14:15], v9, s53, v[8:9]
	v_mad_u64_u32 v[18:19], s[14:15], v16, s53, v[72:73]
	v_lshlrev_b64 v[24:25], s13, v[168:169]
	v_add_u32_e32 v32, s46, v136
	v_lshl_add_u64 v[0:1], v[0:1], 0, v[120:121]
	s_movk_i32 s16, 0x1000
	v_mov_b32_e32 v11, v8
	v_mov_b32_e32 v16, v19
	v_lshl_add_u64 v[24:25], v[24:25], 0, s[38:39]
	v_max_i32_e32 v168, 0, v32
	v_add_co_u32_e32 v4, vcc, s16, v0
	v_lshl_add_u64 v[8:9], v[10:11], 0, s[10:11]
	v_mad_u64_u32 v[16:17], s[14:15], v17, s53, v[16:17]
	v_mad_u64_u32 v[26:27], s[14:15], v24, s53, v[72:73]
	v_lshlrev_b64 v[32:33], s13, v[168:169]
	v_add_u32_e32 v40, s46, v138
	v_addc_co_u32_e32 v5, vcc, 0, v1, vcc
	v_lshl_add_u64 v[8:9], v[8:9], 0, v[120:121]
	v_mov_b32_e32 v19, v16
	v_mov_b32_e32 v24, v27
	v_lshl_add_u64 v[32:33], v[32:33], 0, s[38:39]
	v_max_i32_e32 v168, 0, v40
	v_add_co_u32_e32 v12, vcc, s16, v8
	v_lshl_add_u64 v[16:17], v[18:19], 0, s[10:11]
	v_mad_u64_u32 v[24:25], s[14:15], v25, s53, v[24:25]
	v_mad_u64_u32 v[34:35], s[14:15], v32, s53, v[72:73]
	v_lshlrev_b64 v[40:41], s13, v[168:169]
	v_add_u32_e32 v64, s46, v139
	v_add_u32_e32 v74, s46, v140
	v_addc_co_u32_e32 v13, vcc, 0, v9, vcc
	v_lshl_add_u64 v[16:17], v[16:17], 0, v[120:121]
	v_mov_b32_e32 v27, v24
	v_mov_b32_e32 v32, v35
	v_lshl_add_u64 v[40:41], v[40:41], 0, s[38:39]
	v_ashrrev_i32_e32 v65, 31, v64
	v_ashrrev_i32_e32 v75, 31, v74
	v_add_co_u32_e32 v20, vcc, s16, v16
	v_lshl_add_u64 v[24:25], v[26:27], 0, s[10:11]
	v_mad_u64_u32 v[32:33], s[14:15], v33, s53, v[32:33]
	v_mad_u64_u32 v[42:43], s[14:15], v40, s53, v[72:73]
	v_lshlrev_b64 v[64:65], s13, v[64:65]
	v_lshlrev_b64 v[74:75], s13, v[74:75]
	v_addc_co_u32_e32 v21, vcc, 0, v17, vcc
	v_lshl_add_u64 v[24:25], v[24:25], 0, v[120:121]
	v_mov_b32_e32 v35, v32
	v_mov_b32_e32 v40, v43
	v_lshl_add_u64 v[64:65], v[64:65], 0, s[38:39]
	v_lshl_add_u64 v[74:75], v[74:75], 0, s[38:39]
	v_add_co_u32_e32 v28, vcc, s16, v24
	v_lshl_add_u64 v[32:33], v[34:35], 0, s[10:11]
	v_mad_u64_u32 v[40:41], s[14:15], v41, s53, v[40:41]
	v_mad_u64_u32 v[66:67], s[14:15], v64, s53, v[72:73]
	v_mad_u64_u32 v[72:73], s[14:15], v74, s53, v[72:73]
	v_addc_co_u32_e32 v29, vcc, 0, v25, vcc
	v_lshl_add_u64 v[32:33], v[32:33], 0, v[120:121]
	v_mov_b32_e32 v43, v40
	v_mov_b32_e32 v64, v67
	v_mov_b32_e32 v74, v73
	v_add_co_u32_e32 v36, vcc, s16, v32
	v_lshl_add_u64 v[40:41], v[42:43], 0, s[10:11]
	v_mad_u64_u32 v[64:65], s[14:15], v65, s53, v[64:65]
	v_mad_u64_u32 v[74:75], s[14:15], v75, s53, v[74:75]
	v_addc_co_u32_e32 v37, vcc, 0, v33, vcc
	v_lshl_add_u64 v[40:41], v[40:41], 0, v[120:121]
	v_mov_b32_e32 v67, v64
	v_mov_b32_e32 v73, v74
	v_add_co_u32_e32 v44, vcc, s16, v40
	v_lshl_add_u64 v[64:65], v[66:67], 0, s[10:11]
	v_mov_b32_e32 v123, v169
	v_lshl_add_u64 v[72:73], v[72:73], 0, s[10:11]
	v_addc_co_u32_e32 v45, vcc, 0, v41, vcc
	v_lshl_add_u64 v[64:65], v[64:65], 0, v[122:123]
	v_lshl_add_u64 v[72:73], v[72:73], 0, v[122:123]
	global_load_dwordx4 v[0:3], v[0:1], off offset:3072
	s_nop 0
	global_load_dwordx4 v[4:7], v[4:5], off offset:2048
	s_nop 0
	global_load_dwordx4 v[8:11], v[8:9], off offset:3072
	s_nop 0
	global_load_dwordx4 v[12:15], v[12:13], off offset:2048
	s_nop 0
	global_load_dwordx4 v[16:19], v[16:17], off offset:3072
	s_nop 0
	global_load_dwordx4 v[20:23], v[20:21], off offset:2048
	s_nop 0
	global_load_dwordx4 v[24:27], v[24:25], off offset:3072
	s_nop 0
	global_load_dwordx4 v[28:31], v[28:29], off offset:2048
	s_nop 0
	global_load_dwordx4 v[32:35], v[32:33], off offset:3072
	s_nop 0
	global_load_dwordx4 v[36:39], v[36:37], off offset:2048
	s_nop 0
	global_load_dwordx4 v[40:43], v[40:41], off offset:3072
	s_nop 0
	global_load_dwordx4 v[44:47], v[44:45], off offset:2048
	s_nop 0
	global_load_dwordx4 v[68:71], v[64:65], off
	s_nop 0
	global_load_dwordx4 v[64:67], v[64:65], off offset:64
	s_nop 0
	global_load_dwordx4 v[76:79], v[72:73], off
	s_nop 0
	global_load_dwordx4 v[72:75], v[72:73], off offset:64
	s_lshl_b32 s43, 1, s13
